# CV1: phase-1 e_w_in conversion loop hand-written with two tiles of loads in flight (on top of CV2)
# speedup vs baseline: 1.0070x; 1.0002x over previous
.LBB0_103:
	s_or_saveexec_b64 s[6:7], s[6:7]
	v_and_b32_e32 v1, 63, v0
	s_xor_b64 exec, exec, s[6:7]
	v_lshlrev_b32_e32 v2, 1, v0
	v_lshrrev_b32_e32 v4, 2, v0
	v_and_b32_e32 v2, 24, v2
	v_and_b32_e32 v10, 4, v4
	v_and_b32_e32 v3, 0xffffffe3, v3
	v_or3_b32 v2, v2, v3, v10
	s_or_b64 exec, exec, s[6:7]
	s_and_b32 s0, s0, 0x3fff0
	s_sub_i32 s0, s58, s0
	v_lshrrev_b32_e32 v11, 6, v0
	v_lshl_or_b32 v3, s0, 6, v11
	v_mul_i32_i24_e32 v4, 0x2100, v3
	v_ashrrev_i32_e32 v5, 31, v4
	s_waitcnt lgkmcnt(0)
	v_lshl_add_u64 v[4:5], v[4:5], 2, s[4:5]
	v_ashrrev_i32_e32 v3, 31, v2
	v_lshl_add_u64 v[2:3], v[2:3], 2, v[4:5]
	s_mov_b32 s0, 0x42000
	v_add_co_u32_e32 v6, vcc, s0, v2
	s_mov_b32 s0, 0x84000
	s_nop 0
	v_addc_co_u32_e32 v7, vcc, 0, v3, vcc
	v_add_co_u32_e32 v8, vcc, s0, v2
	s_mov_b32 s0, 0xc6000
	s_nop 0
	v_addc_co_u32_e32 v9, vcc, 0, v3, vcc
	v_add_co_u32_e32 v20, vcc, s0, v2
	s_mov_b32 s0, 0x108000
	s_nop 0
	v_addc_co_u32_e32 v21, vcc, 0, v3, vcc
	v_add_co_u32_e32 v22, vcc, s0, v2
	s_mov_b32 s0, 0x14a000
	s_nop 0
	v_addc_co_u32_e32 v23, vcc, 0, v3, vcc
	v_add_co_u32_e32 v24, vcc, s0, v2
	s_mov_b32 s0, 0x18c000
	s_nop 0
	v_addc_co_u32_e32 v25, vcc, 0, v3, vcc
	v_add_co_u32_e32 v26, vcc, s0, v2
	s_mov_b32 s0, 0x1ce000
	s_nop 0
	v_addc_co_u32_e32 v27, vcc, 0, v3, vcc
	v_add_co_u32_e32 v28, vcc, s0, v2
	s_movk_i32 s0, 0x1100
	s_nop 0
	v_addc_co_u32_e32 v29, vcc, 0, v3, vcc
	global_load_dword v17, v[2:3], off
	global_load_dword v16, v[6:7], off
	global_load_dword v15, v[8:9], off
	global_load_dword v14, v[20:21], off
	global_load_dword v13, v[22:23], off
	global_load_dword v5, v[24:25], off
	global_load_dword v4, v[26:27], off
	global_load_dword v18, v[28:29], off
	v_and_b32_e32 v2, 3, v0
	s_add_u32 s6, s10, 0x800000
	v_or3_b32 v6, v2, v10, s0
	v_lshlrev_b32_e32 v2, 3, v0
	s_addc_u32 s7, s11, 0
	v_lshrrev_b32_e32 v8, 3, v0
	v_and_b32_e32 v2, 56, v2
	s_add_i32 s3, s58, s73
	v_lshlrev_b32_e32 v19, 1, v0
	v_mul_u32_u24_e32 v3, 0x104, v2
	v_lshlrev_b32_e32 v9, 2, v8
	s_mul_i32 s3, s3, 0x84000
	s_movk_i32 s2, 0x2100
	v_lshl_add_u32 v12, v1, 2, 0
	v_add3_u32 v9, 0, v3, v9
	v_mov_b32_e32 v3, 0
	v_mul_u32_u24_e32 v20, 0x104, v11
	v_and_or_b32 v10, v19, 24, v10
	v_mov_b32_e32 v19, s3
	v_and_b32_e32 v7, 31, v0
	s_lshl_b32 s0, s58, 6
	s_lshl_b32 s1, s73, 6
	v_mad_u32_u24 v11, v11, s2, v19
	s_mul_i32 s2, s73, 0x84000
	v_add_u32_e32 v12, v12, v20
	s_movk_i32 s3, 0x10ff
	s_movk_i32 s18, 0x7ff
	s_movk_i32 s19, 0x700
	s_movk_i32 s20, 0xffe3
	s_movk_i32 s21, 0x7fff
	s_mov_b32 s22, 0xffff0000
	v_lshlrev_b32_e32 v2, 1, v2
	s_mov_b32 s24, s58
	v_mov_b32_e32 v19, v3
	v_mov_b32_e32 v20, v3
	v_mov_b32_e32 v21, v3
	v_mov_b32_e32 v22, v3
	v_mov_b32_e32 v23, v3
	v_mov_b32_e32 v24, v3
	v_mov_b32_e32 v25, v3
	v_mov_b32_e32 v26, v3
	s_add_i32 s16, s24, s73
	s_cmpk_gt_i32 s16, 0x83f
	s_cbranch_scc1 .Lcv1_A
	s_ashr_i32 s14, s16, 31
	s_lshr_b32 s14, s14, 28
	s_add_i32 s14, s16, s14
	s_ashr_i32 s25, s14, 4
	s_lshl_b32 s26, s25, 6
	v_or_b32_e32 v100, s26, v1
	s_cmp_gt_i32 s26, s3
	s_cbranch_scc1 .Lcv1_hi_1
	v_and_or_b32 v104, v100, s20, v10
	s_branch .Lcv1_sel_1
.Lcv1_hi_1:
	v_add_u32_e32 v101, 0xffffef00, v100
	v_lshlrev_b32_e32 v100, 1, v100
	s_cmpk_lt_u32 s26, 0x1900
	s_cbranch_scc1 .Lcv1_mid_1
	v_and_b32_e32 v104, 0xffffffe0, v101
	v_add_u32_e32 v104, v6, v104
	v_and_or_b32 v104, v100, 24, v104
	s_branch .Lcv1_sel_1
.Lcv1_mid_1:
	v_and_b32_e32 v104, 0xc0, v100
	s_lshr_b32 s26, s26, 2
	v_and_or_b32 v104, v101, s19, v104
	s_and_b32 s26, s26, 32
	v_or3_b32 v104, v104, s26, v7
	v_add_u32_e32 v104, 0x1100, v104
.Lcv1_sel_1:
	s_mul_i32 s25, s25, 0xff7c0000
	v_add_u32_e32 v102, s25, v11
	v_ashrrev_i32_e32 v103, 31, v102
	v_lshl_add_u64 v[102:103], v[102:103], 2, s[4:5]
	v_ashrrev_i32_e32 v105, 31, v104
	v_lshl_add_u64 v[120:121], v[104:105], 2, v[102:103]
	v_add_co_u32_e32 v122, vcc, 0x42000, v120
	s_nop 1
	v_addc_co_u32_e32 v123, vcc, 0, v121, vcc
	v_add_co_u32_e32 v124, vcc, 0x84000, v120
	s_nop 1
	v_addc_co_u32_e32 v125, vcc, 0, v121, vcc
	v_add_co_u32_e32 v126, vcc, 0xc6000, v120
	s_nop 1
	v_addc_co_u32_e32 v127, vcc, 0, v121, vcc
	v_add_co_u32_e32 v128, vcc, 0x108000, v120
	s_nop 1
	v_addc_co_u32_e32 v129, vcc, 0, v121, vcc
	v_add_co_u32_e32 v130, vcc, 0x14a000, v120
	s_nop 1
	v_addc_co_u32_e32 v131, vcc, 0, v121, vcc
	v_add_co_u32_e32 v132, vcc, 0x18c000, v120
	s_nop 1
	v_addc_co_u32_e32 v133, vcc, 0, v121, vcc
	v_add_co_u32_e32 v134, vcc, 0x1ce000, v120
	s_nop 1
	v_addc_co_u32_e32 v135, vcc, 0, v121, vcc
	global_load_dword v110, v[120:121], off
	global_load_dword v111, v[122:123], off
	global_load_dword v112, v[124:125], off
	global_load_dword v113, v[126:127], off
	global_load_dword v114, v[128:129], off
	global_load_dword v115, v[130:131], off
	global_load_dword v116, v[132:133], off
	global_load_dword v117, v[134:135], off
	v_add_u32_e32 v11, s2, v11
.Lcv1_A:
	s_add_i32 s16, s24, s73
	s_add_i32 s17, s16, s73
	s_cmpk_gt_i32 s16, 0x83f
	s_cbranch_scc0 .Lcv1_A_more
	s_waitcnt vmcnt(0)
.Lcv1_A_more:
	s_waitcnt vmcnt(8)
	ds_write_b32 v12, v17 offset:32768
	ds_write_b32 v12, v16 offset:34848
	ds_write_b32 v12, v15 offset:36928
	ds_write_b32 v12, v14 offset:39008
	ds_write_b32 v12, v13 offset:41088
	ds_write_b32 v12, v5 offset:43168
	ds_write_b32 v12, v4 offset:45248
	ds_write_b32 v12, v18 offset:47328
	s_cmpk_gt_i32 s17, 0x83f
	s_cbranch_scc1 .Lcv1_A_noload
	s_ashr_i32 s14, s17, 31
	s_lshr_b32 s14, s14, 28
	s_add_i32 s14, s17, s14
	s_ashr_i32 s25, s14, 4
	s_lshl_b32 s26, s25, 6
	v_or_b32_e32 v100, s26, v1
	s_cmp_gt_i32 s26, s3
	s_cbranch_scc1 .Lcv1_hi_2
	v_and_or_b32 v104, v100, s20, v10
	s_branch .Lcv1_sel_2

.Lcv1_sel_2:
	s_mul_i32 s25, s25, 0xff7c0000
	v_add_u32_e32 v102, s25, v11
	v_ashrrev_i32_e32 v103, 31, v102
	v_lshl_add_u64 v[102:103], v[102:103], 2, s[4:5]
	v_ashrrev_i32_e32 v105, 31, v104
	v_lshl_add_u64 v[120:121], v[104:105], 2, v[102:103]
	v_add_co_u32_e32 v122, vcc, 0x42000, v120
	s_nop 1
	v_addc_co_u32_e32 v123, vcc, 0, v121, vcc
	v_add_co_u32_e32 v124, vcc, 0x84000, v120
	s_nop 1
	v_addc_co_u32_e32 v125, vcc, 0, v121, vcc
	v_add_co_u32_e32 v126, vcc, 0xc6000, v120
	s_nop 1
	v_addc_co_u32_e32 v127, vcc, 0, v121, vcc
	v_add_co_u32_e32 v128, vcc, 0x108000, v120
	s_nop 1
	v_addc_co_u32_e32 v129, vcc, 0, v121, vcc
	v_add_co_u32_e32 v130, vcc, 0x14a000, v120
	s_nop 1
	v_addc_co_u32_e32 v131, vcc, 0, v121, vcc
	v_add_co_u32_e32 v132, vcc, 0x18c000, v120
	s_nop 1
	v_addc_co_u32_e32 v133, vcc, 0, v121, vcc
	v_add_co_u32_e32 v134, vcc, 0x1ce000, v120
	s_nop 1
	v_addc_co_u32_e32 v135, vcc, 0, v121, vcc
	global_load_dword v17, v[120:121], off
	global_load_dword v16, v[122:123], off
	global_load_dword v15, v[124:125], off
	global_load_dword v14, v[126:127], off
	global_load_dword v13, v[128:129], off
	global_load_dword v5, v[130:131], off
	global_load_dword v4, v[132:133], off
	global_load_dword v18, v[134:135], off
	v_add_u32_e32 v11, s2, v11
.Lcv1_A_noload:
	v_add_u32_e32 v148, 0x8000, v9
	s_waitcnt lgkmcnt(0)
	s_barrier
	ds_read2_b32 v[140:141], v148 offset1:65
	ds_read2_b32 v[142:143], v148 offset0:130 offset1:195
	v_add_u32_e32 v149, 0x8400, v9
	ds_read2_b32 v[144:145], v149 offset0:4 offset1:69
	ds_read2_b32 v[146:147], v149 offset0:134 offset1:199
	s_ashr_i32 s14, s24, 31
	s_lshr_b32 s14, s14, 28
	s_add_i32 s14, s24, s14
	s_ashr_i32 s15, s14, 4
	v_lshl_or_b32 v150, s15, 6, v8
	s_lshl_b32 s14, s15, 10
	v_ashrrev_i32_e32 v151, 31, v150
	s_sub_i32 s14, s0, s14
	v_lshlrev_b64 v[150:151], 11, v[150:151]
	v_lshl_add_u64 v[150:151], s[6:7], 0, v[150:151]
	s_ashr_i32 s15, s14, 31
	v_lshl_add_u64 v[150:151], s[14:15], 1, v[150:151]
	v_lshl_add_u64 v[150:151], v[150:151], 0, v[2:3]
	s_waitcnt lgkmcnt(3)
	v_cvt_pk_bf16_f32 v152, v140, v141
	s_waitcnt lgkmcnt(2)
	v_cvt_pk_bf16_f32 v153, v142, v143
	s_waitcnt lgkmcnt(1)
	v_cvt_pk_bf16_f32 v154, v144, v145
	s_waitcnt lgkmcnt(0)
	v_cvt_pk_bf16_f32 v155, v146, v147
	global_store_dwordx4 v[150:151], v[152:155], off
	s_add_i32 s0, s0, s1
	s_mov_b32 s24, s16
	s_barrier
	s_cmpk_gt_i32 s24, 0x83f
	s_cbranch_scc1 .LBB0_117

.Lcv1_B_more:
	s_waitcnt vmcnt(8)
	ds_write_b32 v12, v110 offset:32768
	ds_write_b32 v12, v111 offset:34848
	ds_write_b32 v12, v112 offset:36928
	ds_write_b32 v12, v113 offset:39008
	ds_write_b32 v12, v114 offset:41088
	ds_write_b32 v12, v115 offset:43168
	ds_write_b32 v12, v116 offset:45248
	ds_write_b32 v12, v117 offset:47328
	s_cmpk_gt_i32 s17, 0x83f
	s_cbranch_scc1 .Lcv1_B_noload
	s_ashr_i32 s14, s17, 31
	s_lshr_b32 s14, s14, 28
	s_add_i32 s14, s17, s14
	s_ashr_i32 s25, s14, 4
	s_lshl_b32 s26, s25, 6
	v_or_b32_e32 v100, s26, v1
	s_cmp_gt_i32 s26, s3
	s_cbranch_scc1 .Lcv1_hi_3
	v_and_or_b32 v104, v100, s20, v10
	s_branch .Lcv1_sel_3

.Lcv1_B_noload:
	v_add_u32_e32 v148, 0x8000, v9
	s_waitcnt lgkmcnt(0)
	s_barrier
	ds_read2_b32 v[140:141], v148 offset1:65
	ds_read2_b32 v[142:143], v148 offset0:130 offset1:195
	v_add_u32_e32 v149, 0x8400, v9
	ds_read2_b32 v[144:145], v149 offset0:4 offset1:69
	ds_read2_b32 v[146:147], v149 offset0:134 offset1:199
	s_ashr_i32 s14, s24, 31
	s_lshr_b32 s14, s14, 28
	s_add_i32 s14, s24, s14
	s_ashr_i32 s15, s14, 4
	v_lshl_or_b32 v150, s15, 6, v8
	s_lshl_b32 s14, s15, 10
	v_ashrrev_i32_e32 v151, 31, v150
	s_sub_i32 s14, s0, s14
	v_lshlrev_b64 v[150:151], 11, v[150:151]
	v_lshl_add_u64 v[150:151], s[6:7], 0, v[150:151]
	s_ashr_i32 s15, s14, 31
	v_lshl_add_u64 v[150:151], s[14:15], 1, v[150:151]
	v_lshl_add_u64 v[150:151], v[150:151], 0, v[2:3]
	s_waitcnt lgkmcnt(3)
	v_cvt_pk_bf16_f32 v152, v140, v141
	s_waitcnt lgkmcnt(2)
	v_cvt_pk_bf16_f32 v153, v142, v143
	s_waitcnt lgkmcnt(1)
	v_cvt_pk_bf16_f32 v154, v144, v145
	s_waitcnt lgkmcnt(0)
	v_cvt_pk_bf16_f32 v155, v146, v147
	global_store_dwordx4 v[150:151], v[152:155], off
	s_add_i32 s0, s0, s1
	s_mov_b32 s24, s16
	s_barrier
	s_cmpk_gt_i32 s24, 0x83f
	s_cbranch_scc1 .LBB0_117
	s_branch .Lcv1_A
